# phase-0 weight conversion (w_in, w_ffn_up) software-pipelined for G==256: next sub-item's 32 row loads issued into a second register set before the current sub-item's LDS transpose and stores; scalar-
# baseline (speedup 1.0000x reference)
.LBB0_25:
	s_lshl_b32 s0, s2, 3
	s_add_i32 s3, s31, s0
	s_mov_b32 s96, s31
	s_cmpk_gt_i32 s3, 0x50ff
	s_cbranch_scc1 .LBB0_39
	s_cmp_lg_u32 s33, 0x100
	s_cbranch_scc1 .Lp0_old
	v_readlane_b32 s22, v255, 14
	v_readlane_b32 s23, v255, 15
	v_readlane_b32 s24, v255, 34
	v_readlane_b32 s25, v255, 35
	v_lshrrev_b32_e32 v79, 5, v174
	v_and_b32_e32 v80, 31, v174
	v_mul_u32_u24_e32 v67, 0x13000, v79
	v_lshl_add_u32 v67, v80, 2, v67
	v_mul_u32_u24_e32 v68, 0x15800, v79
	v_lshl_add_u32 v68, v80, 2, v68
	v_lshrrev_b32_e32 v81, 3, v174
	v_and_b32_e32 v82, 7, v174
	v_lshlrev_b32_e32 v69, 13, v81
	v_lshl_add_u32 v69, v82, 4, v69
	s_mul_i32 s0, s96, 0x3000
	s_add_u32 s0, s0, 0x2000
	v_mul_u32_u24_e32 v83, 33, v79
	v_add_u32_e32 v83, v83, v80
	v_lshl_add_u32 v71, v83, 2, s0
	v_add_u32_e32 v72, 0x420, v71
	v_add_u32_e32 v73, 0x840, v71
	v_add_u32_e32 v74, 0xc60, v71
	v_add_u32_e32 v75, 0x1080, v71
	v_add_u32_e32 v76, 0x14a0, v71
	v_add_u32_e32 v77, 0x18c0, v71
	v_add_u32_e32 v78, 0x1ce0, v71
	v_mul_u32_u24_e32 v83, 264, v82
	v_add_u32_e32 v83, v83, v81
	v_lshl_add_u32 v70, v83, 2, s0
	s_lshl_b32 s3, s2, 3
	s_add_u32 s3, s3, s96
	s_mov_b32 s1, 0
	s_lshl_b32 s16, s1, 6
	s_cmp_lt_u32 s3, 0x2600
	s_cbranch_scc0 .Lp0_up0
	s_mul_hi_u32 s7, s3, 0x6bca1b
	s_mul_i32 s8, s7, 608
	s_sub_u32 s8, s3, s8
	s_lshl_b32 s9, s7, 8
	s_add_u32 s9, s9, s16
	s_mul_i32 s16, s9, 0x13000
	s_lshl_b32 s17, s8, 7
	s_add_u32 s16, s16, s17
	s_add_u32 s4, s22, s16
	s_addc_u32 s5, s23, 0
	s_mov_b32 s6, 0x26000
	v_mov_b32_e32 v66, v67
	s_lshl_b32 s16, s8, 18
	s_lshl_b32 s17, s9, 1
	s_add_u32 s16, s16, s17
	s_add_u32 s16, s16, 0x1200000
	s_add_u32 s12, s70, s16
	s_addc_u32 s13, s71, 0
	s_branch .Lp0_ad0
.Lp0_up0:
	s_sub_u32 s18, s3, 0x2600
	s_mul_hi_u32 s7, s18, 0x5f417e
	s_mul_i32 s8, s7, 688
	s_sub_u32 s8, s18, s8
	s_lshl_b32 s9, s7, 8
	s_add_u32 s9, s9, s16
	s_mul_i32 s16, s9, 0x15800
	s_lshl_b32 s17, s8, 7
	s_add_u32 s16, s16, s17
	s_add_u32 s4, s24, s16
	s_addc_u32 s5, s25, 0
	s_mov_b32 s6, 0x2b000
	v_mov_b32_e32 v66, v68
	s_lshl_b32 s19, s8, 5
	s_mov_b32 s21, 0
	s_cmp_lt_u32 s19, 0x2b00
	s_cbranch_scc1 .Lp0_lo0
	s_sub_u32 s19, s19, 0x2b00
	s_mov_b32 s21, 128
.Lp0_lo0:
	s_lshr_b32 s20, s19, 7
	s_lshl_b32 s20, s20, 8
	s_and_b32 s19, s19, 127
	s_add_u32 s20, s20, s19
	s_add_u32 s20, s20, s21
	s_lshl_b32 s16, s20, 13
	s_lshl_b32 s17, s9, 1
	s_add_u32 s16, s16, s17
	s_add_u32 s16, s16, 0xea00000
	s_add_u32 s12, s70, s16
	s_addc_u32 s13, s71, 0
.Lp0_ad0:
	global_load_dword v2, v66, s[4:5] nt
	s_add_u32 s4, s4, s6
	s_addc_u32 s5, s5, 0
	global_load_dword v3, v66, s[4:5] nt
	s_add_u32 s4, s4, s6
	s_addc_u32 s5, s5, 0
	global_load_dword v4, v66, s[4:5] nt
	s_add_u32 s4, s4, s6
	s_addc_u32 s5, s5, 0
	global_load_dword v5, v66, s[4:5] nt
	s_add_u32 s4, s4, s6
	s_addc_u32 s5, s5, 0
	global_load_dword v6, v66, s[4:5] nt
	s_add_u32 s4, s4, s6
	s_addc_u32 s5, s5, 0
	global_load_dword v7, v66, s[4:5] nt
	s_add_u32 s4, s4, s6
	s_addc_u32 s5, s5, 0
	global_load_dword v8, v66, s[4:5] nt
	s_add_u32 s4, s4, s6
	s_addc_u32 s5, s5, 0
	global_load_dword v9, v66, s[4:5] nt
	s_add_u32 s4, s4, s6
	s_addc_u32 s5, s5, 0
	global_load_dword v10, v66, s[4:5] nt
	s_add_u32 s4, s4, s6
	s_addc_u32 s5, s5, 0
	global_load_dword v11, v66, s[4:5] nt
	s_add_u32 s4, s4, s6
	s_addc_u32 s5, s5, 0
	global_load_dword v12, v66, s[4:5] nt
	s_add_u32 s4, s4, s6
	s_addc_u32 s5, s5, 0
	global_load_dword v13, v66, s[4:5] nt
	s_add_u32 s4, s4, s6
	s_addc_u32 s5, s5, 0
	global_load_dword v14, v66, s[4:5] nt
	s_add_u32 s4, s4, s6
	s_addc_u32 s5, s5, 0
	global_load_dword v15, v66, s[4:5] nt
	s_add_u32 s4, s4, s6
	s_addc_u32 s5, s5, 0
	global_load_dword v16, v66, s[4:5] nt
	s_add_u32 s4, s4, s6
	s_addc_u32 s5, s5, 0
	global_load_dword v17, v66, s[4:5] nt
	s_add_u32 s4, s4, s6
	s_addc_u32 s5, s5, 0
	global_load_dword v18, v66, s[4:5] nt
	s_add_u32 s4, s4, s6
	s_addc_u32 s5, s5, 0
	global_load_dword v19, v66, s[4:5] nt
	s_add_u32 s4, s4, s6
	s_addc_u32 s5, s5, 0
	global_load_dword v20, v66, s[4:5] nt
	s_add_u32 s4, s4, s6
	s_addc_u32 s5, s5, 0
	global_load_dword v21, v66, s[4:5] nt
	s_add_u32 s4, s4, s6
	s_addc_u32 s5, s5, 0
	global_load_dword v22, v66, s[4:5] nt
	s_add_u32 s4, s4, s6
	s_addc_u32 s5, s5, 0
	global_load_dword v23, v66, s[4:5] nt
	s_add_u32 s4, s4, s6
	s_addc_u32 s5, s5, 0
	global_load_dword v24, v66, s[4:5] nt
	s_add_u32 s4, s4, s6
	s_addc_u32 s5, s5, 0
	global_load_dword v25, v66, s[4:5] nt
	s_add_u32 s4, s4, s6
	s_addc_u32 s5, s5, 0
	global_load_dword v26, v66, s[4:5] nt
	s_add_u32 s4, s4, s6
	s_addc_u32 s5, s5, 0
	global_load_dword v27, v66, s[4:5] nt
	s_add_u32 s4, s4, s6
	s_addc_u32 s5, s5, 0
	global_load_dword v28, v66, s[4:5] nt
	s_add_u32 s4, s4, s6
	s_addc_u32 s5, s5, 0
	global_load_dword v29, v66, s[4:5] nt
	s_add_u32 s4, s4, s6
	s_addc_u32 s5, s5, 0
	global_load_dword v30, v66, s[4:5] nt
	s_add_u32 s4, s4, s6
	s_addc_u32 s5, s5, 0
	global_load_dword v31, v66, s[4:5] nt
	s_add_u32 s4, s4, s6
	s_addc_u32 s5, s5, 0
	global_load_dword v32, v66, s[4:5] nt
	s_add_u32 s4, s4, s6
	s_addc_u32 s5, s5, 0
	global_load_dword v33, v66, s[4:5] nt
	s_add_u32 s4, s4, s6
	s_addc_u32 s5, s5, 0
	s_add_u32 s1, s1, 1
	s_cmp_eq_u32 s1, 4
	s_cselect_b32 s16, 0x800, 0
	s_cselect_b32 s1, 0, s1
	s_add_u32 s3, s3, s16
.Lp0_loop:
	s_cmp_lt_u32 s3, 0x5100
	s_cbranch_scc0 .Lp0_lastA
	s_lshl_b32 s16, s1, 6
	s_cmp_lt_u32 s3, 0x2600
	s_cbranch_scc0 .Lp0_up1
	s_mul_hi_u32 s7, s3, 0x6bca1b
	s_mul_i32 s8, s7, 608
	s_sub_u32 s8, s3, s8
	s_lshl_b32 s9, s7, 8
	s_add_u32 s9, s9, s16
	s_mul_i32 s16, s9, 0x13000
	s_lshl_b32 s17, s8, 7
	s_add_u32 s16, s16, s17
	s_add_u32 s4, s22, s16
	s_addc_u32 s5, s23, 0
	s_mov_b32 s6, 0x26000
	v_mov_b32_e32 v66, v67
	s_lshl_b32 s16, s8, 18
	s_lshl_b32 s17, s9, 1
	s_add_u32 s16, s16, s17
	s_add_u32 s16, s16, 0x1200000
	s_add_u32 s14, s70, s16
	s_addc_u32 s15, s71, 0
	s_branch .Lp0_ad1

.Lp0_lo1:
	s_lshr_b32 s20, s19, 7
	s_lshl_b32 s20, s20, 8
	s_and_b32 s19, s19, 127
	s_add_u32 s20, s20, s19
	s_add_u32 s20, s20, s21
	s_lshl_b32 s16, s20, 13
	s_lshl_b32 s17, s9, 1
	s_add_u32 s16, s16, s17
	s_add_u32 s16, s16, 0xea00000
	s_add_u32 s14, s70, s16
	s_addc_u32 s15, s71, 0
.Lp0_ad1:
	global_load_dword v34, v66, s[4:5] nt
	s_add_u32 s4, s4, s6
	s_addc_u32 s5, s5, 0
	global_load_dword v35, v66, s[4:5] nt
	s_add_u32 s4, s4, s6
	s_addc_u32 s5, s5, 0
	global_load_dword v36, v66, s[4:5] nt
	s_add_u32 s4, s4, s6
	s_addc_u32 s5, s5, 0
	global_load_dword v37, v66, s[4:5] nt
	s_add_u32 s4, s4, s6
	s_addc_u32 s5, s5, 0
	global_load_dword v38, v66, s[4:5] nt
	s_add_u32 s4, s4, s6
	s_addc_u32 s5, s5, 0
	global_load_dword v39, v66, s[4:5] nt
	s_add_u32 s4, s4, s6
	s_addc_u32 s5, s5, 0
	global_load_dword v40, v66, s[4:5] nt
	s_add_u32 s4, s4, s6
	s_addc_u32 s5, s5, 0
	global_load_dword v41, v66, s[4:5] nt
	s_add_u32 s4, s4, s6
	s_addc_u32 s5, s5, 0
	global_load_dword v42, v66, s[4:5] nt
	s_add_u32 s4, s4, s6
	s_addc_u32 s5, s5, 0
	global_load_dword v43, v66, s[4:5] nt
	s_add_u32 s4, s4, s6
	s_addc_u32 s5, s5, 0
	global_load_dword v44, v66, s[4:5] nt
	s_add_u32 s4, s4, s6
	s_addc_u32 s5, s5, 0
	global_load_dword v45, v66, s[4:5] nt
	s_add_u32 s4, s4, s6
	s_addc_u32 s5, s5, 0
	global_load_dword v46, v66, s[4:5] nt
	s_add_u32 s4, s4, s6
	s_addc_u32 s5, s5, 0
	global_load_dword v47, v66, s[4:5] nt
	s_add_u32 s4, s4, s6
	s_addc_u32 s5, s5, 0
	global_load_dword v48, v66, s[4:5] nt
	s_add_u32 s4, s4, s6
	s_addc_u32 s5, s5, 0
	global_load_dword v49, v66, s[4:5] nt
	s_add_u32 s4, s4, s6
	s_addc_u32 s5, s5, 0
	global_load_dword v50, v66, s[4:5] nt
	s_add_u32 s4, s4, s6
	s_addc_u32 s5, s5, 0
	global_load_dword v51, v66, s[4:5] nt
	s_add_u32 s4, s4, s6
	s_addc_u32 s5, s5, 0
	global_load_dword v52, v66, s[4:5] nt
	s_add_u32 s4, s4, s6
	s_addc_u32 s5, s5, 0
	global_load_dword v53, v66, s[4:5] nt
	s_add_u32 s4, s4, s6
	s_addc_u32 s5, s5, 0
	global_load_dword v54, v66, s[4:5] nt
	s_add_u32 s4, s4, s6
	s_addc_u32 s5, s5, 0
	global_load_dword v55, v66, s[4:5] nt
	s_add_u32 s4, s4, s6
	s_addc_u32 s5, s5, 0
	global_load_dword v56, v66, s[4:5] nt
	s_add_u32 s4, s4, s6
	s_addc_u32 s5, s5, 0
	global_load_dword v57, v66, s[4:5] nt
	s_add_u32 s4, s4, s6
	s_addc_u32 s5, s5, 0
	global_load_dword v58, v66, s[4:5] nt
	s_add_u32 s4, s4, s6
	s_addc_u32 s5, s5, 0
	global_load_dword v59, v66, s[4:5] nt
	s_add_u32 s4, s4, s6
	s_addc_u32 s5, s5, 0
	global_load_dword v60, v66, s[4:5] nt
	s_add_u32 s4, s4, s6
	s_addc_u32 s5, s5, 0
	global_load_dword v61, v66, s[4:5] nt
	s_add_u32 s4, s4, s6
	s_addc_u32 s5, s5, 0
	global_load_dword v62, v66, s[4:5] nt
	s_add_u32 s4, s4, s6
	s_addc_u32 s5, s5, 0
	global_load_dword v63, v66, s[4:5] nt
	s_add_u32 s4, s4, s6
	s_addc_u32 s5, s5, 0
	global_load_dword v64, v66, s[4:5] nt
	s_add_u32 s4, s4, s6
	s_addc_u32 s5, s5, 0
	global_load_dword v65, v66, s[4:5] nt
	s_add_u32 s4, s4, s6
	s_addc_u32 s5, s5, 0
	s_add_u32 s1, s1, 1
	s_cmp_eq_u32 s1, 4
	s_cselect_b32 s16, 0x800, 0
	s_cselect_b32 s1, 0, s1
	s_add_u32 s3, s3, s16
	s_waitcnt vmcnt(32)
	ds_write2_b32 v71, v2, v3 offset1:66
	ds_write2_b32 v71, v4, v5 offset0:132 offset1:198
	ds_write2_b32 v72, v6, v7 offset1:66
	ds_write2_b32 v72, v8, v9 offset0:132 offset1:198
	ds_write2_b32 v73, v10, v11 offset1:66
	ds_write2_b32 v73, v12, v13 offset0:132 offset1:198
	ds_write2_b32 v74, v14, v15 offset1:66
	ds_write2_b32 v74, v16, v17 offset0:132 offset1:198
	ds_write2_b32 v75, v18, v19 offset1:66
	ds_write2_b32 v75, v20, v21 offset0:132 offset1:198
	ds_write2_b32 v76, v22, v23 offset1:66
	ds_write2_b32 v76, v24, v25 offset0:132 offset1:198
	ds_write2_b32 v77, v26, v27 offset1:66
	ds_write2_b32 v77, v28, v29 offset0:132 offset1:198
	ds_write2_b32 v78, v30, v31 offset1:66
	ds_write2_b32 v78, v32, v33 offset0:132 offset1:198
	s_waitcnt lgkmcnt(0)
	ds_read2_b32 v[88:89], v70 offset0:0 offset1:33
	ds_read2_b32 v[90:91], v70 offset0:66 offset1:99
	ds_read2_b32 v[92:93], v70 offset0:132 offset1:165
	ds_read2_b32 v[94:95], v70 offset0:198 offset1:231
	ds_read2_b32 v[96:97], v70 offset0:8 offset1:41
	ds_read2_b32 v[98:99], v70 offset0:74 offset1:107
	ds_read2_b32 v[100:101], v70 offset0:140 offset1:173
	ds_read2_b32 v[102:103], v70 offset0:206 offset1:239
	ds_read2_b32 v[104:105], v70 offset0:16 offset1:49
	ds_read2_b32 v[106:107], v70 offset0:82 offset1:115
	ds_read2_b32 v[108:109], v70 offset0:148 offset1:181
	ds_read2_b32 v[110:111], v70 offset0:214 offset1:247
	ds_read2_b32 v[112:113], v70 offset0:24 offset1:57
	ds_read2_b32 v[114:115], v70 offset0:90 offset1:123
	ds_read2_b32 v[116:117], v70 offset0:156 offset1:189
	ds_read2_b32 v[118:119], v70 offset0:222 offset1:255
	s_waitcnt lgkmcnt(12)
	v_cvt_pk_bf16_f32 v120, v88, v89
	v_cvt_pk_bf16_f32 v121, v90, v91
	v_cvt_pk_bf16_f32 v122, v92, v93
	v_cvt_pk_bf16_f32 v123, v94, v95
	global_store_dwordx4 v69, v[120:123], s[12:13]
	s_add_u32 s12, s12, 0x10000
	s_addc_u32 s13, s13, 0
	s_waitcnt lgkmcnt(8)
	v_cvt_pk_bf16_f32 v124, v96, v97
	v_cvt_pk_bf16_f32 v125, v98, v99
	v_cvt_pk_bf16_f32 v126, v100, v101
	v_cvt_pk_bf16_f32 v127, v102, v103
	global_store_dwordx4 v69, v[124:127], s[12:13]
	s_add_u32 s12, s12, 0x10000
	s_addc_u32 s13, s13, 0
	s_waitcnt lgkmcnt(4)
	v_cvt_pk_bf16_f32 v120, v104, v105
	v_cvt_pk_bf16_f32 v121, v106, v107
	v_cvt_pk_bf16_f32 v122, v108, v109
	v_cvt_pk_bf16_f32 v123, v110, v111
	global_store_dwordx4 v69, v[120:123], s[12:13]
	s_add_u32 s12, s12, 0x10000
	s_addc_u32 s13, s13, 0
	s_waitcnt lgkmcnt(0)
	v_cvt_pk_bf16_f32 v124, v112, v113
	v_cvt_pk_bf16_f32 v125, v114, v115
	v_cvt_pk_bf16_f32 v126, v116, v117
	v_cvt_pk_bf16_f32 v127, v118, v119
	global_store_dwordx4 v69, v[124:127], s[12:13]
	s_cmp_lt_u32 s3, 0x5100
	s_cbranch_scc0 .Lp0_lastB
	s_lshl_b32 s16, s1, 6
	s_cmp_lt_u32 s3, 0x2600
	s_cbranch_scc0 .Lp0_up2
	s_mul_hi_u32 s7, s3, 0x6bca1b
	s_mul_i32 s8, s7, 608
	s_sub_u32 s8, s3, s8
	s_lshl_b32 s9, s7, 8
	s_add_u32 s9, s9, s16
	s_mul_i32 s16, s9, 0x13000
	s_lshl_b32 s17, s8, 7
	s_add_u32 s16, s16, s17
	s_add_u32 s4, s22, s16
	s_addc_u32 s5, s23, 0
	s_mov_b32 s6, 0x26000
	v_mov_b32_e32 v66, v67
	s_lshl_b32 s16, s8, 18
	s_lshl_b32 s17, s9, 1
	s_add_u32 s16, s16, s17
	s_add_u32 s16, s16, 0x1200000
	s_add_u32 s12, s70, s16
	s_addc_u32 s13, s71, 0
	s_branch .Lp0_ad2

.Lp0_ad2:
	global_load_dword v2, v66, s[4:5] nt
	s_add_u32 s4, s4, s6
	s_addc_u32 s5, s5, 0
	global_load_dword v3, v66, s[4:5] nt
	s_add_u32 s4, s4, s6
	s_addc_u32 s5, s5, 0
	global_load_dword v4, v66, s[4:5] nt
	s_add_u32 s4, s4, s6
	s_addc_u32 s5, s5, 0
	global_load_dword v5, v66, s[4:5] nt
	s_add_u32 s4, s4, s6
	s_addc_u32 s5, s5, 0
	global_load_dword v6, v66, s[4:5] nt
	s_add_u32 s4, s4, s6
	s_addc_u32 s5, s5, 0
	global_load_dword v7, v66, s[4:5] nt
	s_add_u32 s4, s4, s6
	s_addc_u32 s5, s5, 0
	global_load_dword v8, v66, s[4:5] nt
	s_add_u32 s4, s4, s6
	s_addc_u32 s5, s5, 0
	global_load_dword v9, v66, s[4:5] nt
	s_add_u32 s4, s4, s6
	s_addc_u32 s5, s5, 0
	global_load_dword v10, v66, s[4:5] nt
	s_add_u32 s4, s4, s6
	s_addc_u32 s5, s5, 0
	global_load_dword v11, v66, s[4:5] nt
	s_add_u32 s4, s4, s6
	s_addc_u32 s5, s5, 0
	global_load_dword v12, v66, s[4:5] nt
	s_add_u32 s4, s4, s6
	s_addc_u32 s5, s5, 0
	global_load_dword v13, v66, s[4:5] nt
	s_add_u32 s4, s4, s6
	s_addc_u32 s5, s5, 0
	global_load_dword v14, v66, s[4:5] nt
	s_add_u32 s4, s4, s6
	s_addc_u32 s5, s5, 0
	global_load_dword v15, v66, s[4:5] nt
	s_add_u32 s4, s4, s6
	s_addc_u32 s5, s5, 0
	global_load_dword v16, v66, s[4:5] nt
	s_add_u32 s4, s4, s6
	s_addc_u32 s5, s5, 0
	global_load_dword v17, v66, s[4:5] nt
	s_add_u32 s4, s4, s6
	s_addc_u32 s5, s5, 0
	global_load_dword v18, v66, s[4:5] nt
	s_add_u32 s4, s4, s6
	s_addc_u32 s5, s5, 0
	global_load_dword v19, v66, s[4:5] nt
	s_add_u32 s4, s4, s6
	s_addc_u32 s5, s5, 0
	global_load_dword v20, v66, s[4:5] nt
	s_add_u32 s4, s4, s6
	s_addc_u32 s5, s5, 0
	global_load_dword v21, v66, s[4:5] nt
	s_add_u32 s4, s4, s6
	s_addc_u32 s5, s5, 0
	global_load_dword v22, v66, s[4:5] nt
	s_add_u32 s4, s4, s6
	s_addc_u32 s5, s5, 0
	global_load_dword v23, v66, s[4:5] nt
	s_add_u32 s4, s4, s6
	s_addc_u32 s5, s5, 0
	global_load_dword v24, v66, s[4:5] nt
	s_add_u32 s4, s4, s6
	s_addc_u32 s5, s5, 0
	global_load_dword v25, v66, s[4:5] nt
	s_add_u32 s4, s4, s6
	s_addc_u32 s5, s5, 0
	global_load_dword v26, v66, s[4:5] nt
	s_add_u32 s4, s4, s6
	s_addc_u32 s5, s5, 0
	global_load_dword v27, v66, s[4:5] nt
	s_add_u32 s4, s4, s6
	s_addc_u32 s5, s5, 0
	global_load_dword v28, v66, s[4:5] nt
	s_add_u32 s4, s4, s6
	s_addc_u32 s5, s5, 0
	global_load_dword v29, v66, s[4:5] nt
	s_add_u32 s4, s4, s6
	s_addc_u32 s5, s5, 0
	global_load_dword v30, v66, s[4:5] nt
	s_add_u32 s4, s4, s6
	s_addc_u32 s5, s5, 0
	global_load_dword v31, v66, s[4:5] nt
	s_add_u32 s4, s4, s6
	s_addc_u32 s5, s5, 0
	global_load_dword v32, v66, s[4:5] nt
	s_add_u32 s4, s4, s6
	s_addc_u32 s5, s5, 0
	global_load_dword v33, v66, s[4:5] nt
	s_add_u32 s4, s4, s6
	s_addc_u32 s5, s5, 0
	s_add_u32 s1, s1, 1
	s_cmp_eq_u32 s1, 4
	s_cselect_b32 s16, 0x800, 0
	s_cselect_b32 s1, 0, s1
	s_add_u32 s3, s3, s16
	s_waitcnt vmcnt(32)
	ds_write2_b32 v71, v34, v35 offset1:66
	ds_write2_b32 v71, v36, v37 offset0:132 offset1:198
	ds_write2_b32 v72, v38, v39 offset1:66
	ds_write2_b32 v72, v40, v41 offset0:132 offset1:198
	ds_write2_b32 v73, v42, v43 offset1:66
	ds_write2_b32 v73, v44, v45 offset0:132 offset1:198
	ds_write2_b32 v74, v46, v47 offset1:66
	ds_write2_b32 v74, v48, v49 offset0:132 offset1:198
	ds_write2_b32 v75, v50, v51 offset1:66
	ds_write2_b32 v75, v52, v53 offset0:132 offset1:198
	ds_write2_b32 v76, v54, v55 offset1:66
	ds_write2_b32 v76, v56, v57 offset0:132 offset1:198
	ds_write2_b32 v77, v58, v59 offset1:66
	ds_write2_b32 v77, v60, v61 offset0:132 offset1:198
	ds_write2_b32 v78, v62, v63 offset1:66
	ds_write2_b32 v78, v64, v65 offset0:132 offset1:198
	s_waitcnt lgkmcnt(0)
	ds_read2_b32 v[88:89], v70 offset0:0 offset1:33
	ds_read2_b32 v[90:91], v70 offset0:66 offset1:99
	ds_read2_b32 v[92:93], v70 offset0:132 offset1:165
	ds_read2_b32 v[94:95], v70 offset0:198 offset1:231
	ds_read2_b32 v[96:97], v70 offset0:8 offset1:41
	ds_read2_b32 v[98:99], v70 offset0:74 offset1:107
	ds_read2_b32 v[100:101], v70 offset0:140 offset1:173
	ds_read2_b32 v[102:103], v70 offset0:206 offset1:239
	ds_read2_b32 v[104:105], v70 offset0:16 offset1:49
	ds_read2_b32 v[106:107], v70 offset0:82 offset1:115
	ds_read2_b32 v[108:109], v70 offset0:148 offset1:181
	ds_read2_b32 v[110:111], v70 offset0:214 offset1:247
	ds_read2_b32 v[112:113], v70 offset0:24 offset1:57
	ds_read2_b32 v[114:115], v70 offset0:90 offset1:123
	ds_read2_b32 v[116:117], v70 offset0:156 offset1:189
	ds_read2_b32 v[118:119], v70 offset0:222 offset1:255
	s_waitcnt lgkmcnt(12)
	v_cvt_pk_bf16_f32 v120, v88, v89
	v_cvt_pk_bf16_f32 v121, v90, v91
	v_cvt_pk_bf16_f32 v122, v92, v93
	v_cvt_pk_bf16_f32 v123, v94, v95
	global_store_dwordx4 v69, v[120:123], s[14:15]
	s_add_u32 s14, s14, 0x10000
	s_addc_u32 s15, s15, 0
	s_waitcnt lgkmcnt(8)
	v_cvt_pk_bf16_f32 v124, v96, v97
	v_cvt_pk_bf16_f32 v125, v98, v99
	v_cvt_pk_bf16_f32 v126, v100, v101
	v_cvt_pk_bf16_f32 v127, v102, v103
	global_store_dwordx4 v69, v[124:127], s[14:15]
	s_add_u32 s14, s14, 0x10000
	s_addc_u32 s15, s15, 0
	s_waitcnt lgkmcnt(4)
	v_cvt_pk_bf16_f32 v120, v104, v105
	v_cvt_pk_bf16_f32 v121, v106, v107
	v_cvt_pk_bf16_f32 v122, v108, v109
	v_cvt_pk_bf16_f32 v123, v110, v111
	global_store_dwordx4 v69, v[120:123], s[14:15]
	s_add_u32 s14, s14, 0x10000
	s_addc_u32 s15, s15, 0
	s_waitcnt lgkmcnt(0)
	v_cvt_pk_bf16_f32 v124, v112, v113
	v_cvt_pk_bf16_f32 v125, v114, v115
	v_cvt_pk_bf16_f32 v126, v116, v117
	v_cvt_pk_bf16_f32 v127, v118, v119
	global_store_dwordx4 v69, v[124:127], s[14:15]
	s_branch .Lp0_loop
.Lp0_lastA:
	s_waitcnt vmcnt(0)
	ds_write2_b32 v71, v2, v3 offset1:66
	ds_write2_b32 v71, v4, v5 offset0:132 offset1:198
	ds_write2_b32 v72, v6, v7 offset1:66
	ds_write2_b32 v72, v8, v9 offset0:132 offset1:198
	ds_write2_b32 v73, v10, v11 offset1:66
	ds_write2_b32 v73, v12, v13 offset0:132 offset1:198
	ds_write2_b32 v74, v14, v15 offset1:66
	ds_write2_b32 v74, v16, v17 offset0:132 offset1:198
	ds_write2_b32 v75, v18, v19 offset1:66
	ds_write2_b32 v75, v20, v21 offset0:132 offset1:198
	ds_write2_b32 v76, v22, v23 offset1:66
	ds_write2_b32 v76, v24, v25 offset0:132 offset1:198
	ds_write2_b32 v77, v26, v27 offset1:66
	ds_write2_b32 v77, v28, v29 offset0:132 offset1:198
	ds_write2_b32 v78, v30, v31 offset1:66
	ds_write2_b32 v78, v32, v33 offset0:132 offset1:198
	s_waitcnt lgkmcnt(0)
	ds_read2_b32 v[88:89], v70 offset0:0 offset1:33
	ds_read2_b32 v[90:91], v70 offset0:66 offset1:99
	ds_read2_b32 v[92:93], v70 offset0:132 offset1:165
	ds_read2_b32 v[94:95], v70 offset0:198 offset1:231
	ds_read2_b32 v[96:97], v70 offset0:8 offset1:41
	ds_read2_b32 v[98:99], v70 offset0:74 offset1:107
	ds_read2_b32 v[100:101], v70 offset0:140 offset1:173
	ds_read2_b32 v[102:103], v70 offset0:206 offset1:239
	ds_read2_b32 v[104:105], v70 offset0:16 offset1:49
	ds_read2_b32 v[106:107], v70 offset0:82 offset1:115
	ds_read2_b32 v[108:109], v70 offset0:148 offset1:181
	ds_read2_b32 v[110:111], v70 offset0:214 offset1:247
	ds_read2_b32 v[112:113], v70 offset0:24 offset1:57
	ds_read2_b32 v[114:115], v70 offset0:90 offset1:123
	ds_read2_b32 v[116:117], v70 offset0:156 offset1:189
	ds_read2_b32 v[118:119], v70 offset0:222 offset1:255
	s_waitcnt lgkmcnt(12)
	v_cvt_pk_bf16_f32 v120, v88, v89
	v_cvt_pk_bf16_f32 v121, v90, v91
	v_cvt_pk_bf16_f32 v122, v92, v93
	v_cvt_pk_bf16_f32 v123, v94, v95
	global_store_dwordx4 v69, v[120:123], s[12:13]
	s_add_u32 s12, s12, 0x10000
	s_addc_u32 s13, s13, 0
	s_waitcnt lgkmcnt(8)
	v_cvt_pk_bf16_f32 v124, v96, v97
	v_cvt_pk_bf16_f32 v125, v98, v99
	v_cvt_pk_bf16_f32 v126, v100, v101
	v_cvt_pk_bf16_f32 v127, v102, v103
	global_store_dwordx4 v69, v[124:127], s[12:13]
	s_add_u32 s12, s12, 0x10000
	s_addc_u32 s13, s13, 0
	s_waitcnt lgkmcnt(4)
	v_cvt_pk_bf16_f32 v120, v104, v105
	v_cvt_pk_bf16_f32 v121, v106, v107
	v_cvt_pk_bf16_f32 v122, v108, v109
	v_cvt_pk_bf16_f32 v123, v110, v111
	global_store_dwordx4 v69, v[120:123], s[12:13]
	s_add_u32 s12, s12, 0x10000
	s_addc_u32 s13, s13, 0
	s_waitcnt lgkmcnt(0)
	v_cvt_pk_bf16_f32 v124, v112, v113
	v_cvt_pk_bf16_f32 v125, v114, v115
	v_cvt_pk_bf16_f32 v126, v116, v117
	v_cvt_pk_bf16_f32 v127, v118, v119
	global_store_dwordx4 v69, v[124:127], s[12:13]
	s_branch .Lp0_done
.Lp0_lastB:
	s_waitcnt vmcnt(0)
	ds_write2_b32 v71, v34, v35 offset1:66
	ds_write2_b32 v71, v36, v37 offset0:132 offset1:198
	ds_write2_b32 v72, v38, v39 offset1:66
	ds_write2_b32 v72, v40, v41 offset0:132 offset1:198
	ds_write2_b32 v73, v42, v43 offset1:66
	ds_write2_b32 v73, v44, v45 offset0:132 offset1:198
	ds_write2_b32 v74, v46, v47 offset1:66
	ds_write2_b32 v74, v48, v49 offset0:132 offset1:198
	ds_write2_b32 v75, v50, v51 offset1:66
	ds_write2_b32 v75, v52, v53 offset0:132 offset1:198
	ds_write2_b32 v76, v54, v55 offset1:66
	ds_write2_b32 v76, v56, v57 offset0:132 offset1:198
	ds_write2_b32 v77, v58, v59 offset1:66
	ds_write2_b32 v77, v60, v61 offset0:132 offset1:198
	ds_write2_b32 v78, v62, v63 offset1:66
	ds_write2_b32 v78, v64, v65 offset0:132 offset1:198
	s_waitcnt lgkmcnt(0)
	ds_read2_b32 v[88:89], v70 offset0:0 offset1:33
	ds_read2_b32 v[90:91], v70 offset0:66 offset1:99
	ds_read2_b32 v[92:93], v70 offset0:132 offset1:165
	ds_read2_b32 v[94:95], v70 offset0:198 offset1:231
	ds_read2_b32 v[96:97], v70 offset0:8 offset1:41
	ds_read2_b32 v[98:99], v70 offset0:74 offset1:107
	ds_read2_b32 v[100:101], v70 offset0:140 offset1:173
	ds_read2_b32 v[102:103], v70 offset0:206 offset1:239
	ds_read2_b32 v[104:105], v70 offset0:16 offset1:49
	ds_read2_b32 v[106:107], v70 offset0:82 offset1:115
	ds_read2_b32 v[108:109], v70 offset0:148 offset1:181
	ds_read2_b32 v[110:111], v70 offset0:214 offset1:247
	ds_read2_b32 v[112:113], v70 offset0:24 offset1:57
	ds_read2_b32 v[114:115], v70 offset0:90 offset1:123
	ds_read2_b32 v[116:117], v70 offset0:156 offset1:189
	ds_read2_b32 v[118:119], v70 offset0:222 offset1:255
	s_waitcnt lgkmcnt(12)
	v_cvt_pk_bf16_f32 v120, v88, v89
	v_cvt_pk_bf16_f32 v121, v90, v91
	v_cvt_pk_bf16_f32 v122, v92, v93
	v_cvt_pk_bf16_f32 v123, v94, v95
	global_store_dwordx4 v69, v[120:123], s[14:15]
	s_add_u32 s14, s14, 0x10000
	s_addc_u32 s15, s15, 0
	s_waitcnt lgkmcnt(8)
	v_cvt_pk_bf16_f32 v124, v96, v97
	v_cvt_pk_bf16_f32 v125, v98, v99
	v_cvt_pk_bf16_f32 v126, v100, v101
	v_cvt_pk_bf16_f32 v127, v102, v103
	global_store_dwordx4 v69, v[124:127], s[14:15]
	s_add_u32 s14, s14, 0x10000
	s_addc_u32 s15, s15, 0
	s_waitcnt lgkmcnt(4)
	v_cvt_pk_bf16_f32 v120, v104, v105
	v_cvt_pk_bf16_f32 v121, v106, v107
	v_cvt_pk_bf16_f32 v122, v108, v109
	v_cvt_pk_bf16_f32 v123, v110, v111
	global_store_dwordx4 v69, v[120:123], s[14:15]
	s_add_u32 s14, s14, 0x10000
	s_addc_u32 s15, s15, 0
	s_waitcnt lgkmcnt(0)
	v_cvt_pk_bf16_f32 v124, v112, v113
	v_cvt_pk_bf16_f32 v125, v114, v115
	v_cvt_pk_bf16_f32 v126, v116, v117
	v_cvt_pk_bf16_f32 v127, v118, v119
	global_store_dwordx4 v69, v[124:127], s[14:15]

.Lp0_old:
	v_and_b32_e32 v2, 31, v0
	v_readlane_b32 s12, v255, 22
	s_mul_i32 s0, s96, 0x3000
	v_lshlrev_b32_e32 v2, 2, v2
	v_mov_b32_e32 v3, 0
	v_readlane_b32 s13, v255, 23
	v_readlane_b32 s14, v255, 24
	v_readlane_b32 s15, v255, 25
	v_readlane_b32 s16, v255, 26
	v_readlane_b32 s17, v255, 27
	v_readlane_b32 s18, v255, 28
	v_readlane_b32 s19, v255, 29
	v_readlane_b32 s20, v255, 30
	v_readlane_b32 s21, v255, 31
	v_readlane_b32 s22, v255, 32
	v_readlane_b32 s23, v255, 33
	v_readlane_b32 s24, v255, 34
	v_readlane_b32 s25, v255, 35
	v_readlane_b32 s26, v255, 36
	v_readlane_b32 s27, v255, 37
	v_lshlrev_b32_e32 v6, 3, v0
	s_add_i32 s0, s0, 0
	v_lshrrev_b32_e32 v1, 5, v174
	v_lshl_add_u64 v[4:5], s[24:25], 0, v[2:3]
	v_lshrrev_b32_e32 v12, 3, v174
	v_and_b32_e32 v6, 56, v6
	v_readlane_b32 s12, v255, 2
	v_add_u32_e32 v16, s0, v2
	v_mul_u32_u24_e32 v17, 0x84, v1
	v_mul_u32_u24_e32 v8, 0x84, v6
	v_readlane_b32 s4, v255, 39
	v_lshlrev_b32_e32 v9, 2, v12
	v_readlane_b32 s24, v255, 14
	v_readlane_b32 s25, v255, 15
	v_lshlrev_b32_e32 v10, 1, v6
	v_mov_b32_e32 v11, v3
	v_readlane_b32 s5, v255, 40
	v_add3_u32 v24, s0, v8, v9
	v_lshl_add_u64 v[8:9], s[24:25], 0, v[2:3]
	v_add_u32_e32 v2, v16, v17
	s_lshl_b32 s8, s33, 3
	s_mov_b32 s1, 0
	v_lshl_add_u64 v[6:7], s[4:5], 0, v[10:11]
	v_or_b32_e32 v13, 8, v12
	v_or_b32_e32 v14, 16, v12
	v_or_b32_e32 v15, 24, v12
	v_lshl_add_u64 v[10:11], s[86:87], 0, v[10:11]
	s_add_i32 s9, s3, 0xffffda00
	s_mov_b32 s10, 0x15800
	s_mov_b32 s11, 0x13000
	v_add_u32_e32 v16, 0x2000, v2
	v_add_u32_e32 v17, 0x2400, v2
	v_add_u32_e32 v18, 0x2800, v2
	v_add_u32_e32 v19, 0x2c00, v2
	v_add_u32_e32 v20, 0x3000, v2
	v_add_u32_e32 v21, 0x3400, v2
	v_add_u32_e32 v22, 0x3800, v2
	v_add_u32_e32 v23, 0x3c00, v2
	v_add_u32_e32 v24, 0x2000, v24
	v_readlane_b32 s13, v255, 3
	v_readlane_b32 s14, v255, 4
	v_readlane_b32 s15, v255, 5
	v_readlane_b32 s16, v255, 6
	v_readlane_b32 s17, v255, 7
	v_readlane_b32 s18, v255, 8
	v_readlane_b32 s19, v255, 9
	v_readlane_b32 s20, v255, 10
	v_readlane_b32 s21, v255, 11
	v_readlane_b32 s22, v255, 12
	v_readlane_b32 s23, v255, 13
	v_readlane_b32 s26, v255, 16
	v_readlane_b32 s27, v255, 17
	s_branch .LBB0_28
